# P2a work split: per-batch item order row 0, row 127, row 1, row 126, ... so short rows no longer pile up on the first workgroups (P2a prologue map + P2b partial-list lookup changed together)
# speedup vs baseline: 1.0338x; 1.0338x over previous
.LBB0_568:
	s_cmpk_gt_i32 s60, 0x203f
	s_cselect_b64 s[10:11], -1, 0
	s_and_b64 s[0:1], s[10:11], exec
	s_cselect_b32 s18, 0x2040, 0
	s_sub_i32 s2, s60, s18
	s_mul_i32 s0, s2, 0x3f81
	s_lshr_b32 s0, s0, 21
	s_mul_i32 s1, s0, 0x81
	s_sub_i32 s3, s2, s1
	s_sub_i32 s29, 0x7f, s0
	s_add_i32 s59, s1, s0
	s_add_i32 s59, s59, 1
	s_cmp_le_i32 s3, s0
	s_cselect_b32 s17, s0, s29
	s_cselect_b32 s59, s1, s59
	s_add_i32 s5, s17, 1
	s_mov_b32 s29, s17
	s_and_b64 s[0:1], s[10:11], exec
	s_cselect_b32 s6, 0x2000, 0
	s_lshl_b32 s3, s17, 6
	s_add_i32 s7, s3, s6
	v_add_u32_e32 v2, s7, v173
	v_mad_i64_i32 v[0:1], s[0:1], v2, s4, v[120:121]
	global_load_dwordx4 v[72:75], v[0:1], off offset:3072
	global_load_dwordx4 v[76:79], v[0:1], off offset:3104
	global_load_dwordx4 v[80:83], v[0:1], off offset:3136
	global_load_dwordx4 v[84:87], v[0:1], off offset:3168
	v_or_b32_e32 v0, 4, v2
	v_mad_i64_i32 v[0:1], s[0:1], v0, s4, v[120:121]
	global_load_dwordx4 v[88:91], v[0:1], off offset:3072
	global_load_dwordx4 v[92:95], v[0:1], off offset:3104
	global_load_dwordx4 v[96:99], v[0:1], off offset:3136
	global_load_dwordx4 v[100:103], v[0:1], off offset:3168
	v_add_u32_e32 v0, s7, v174
	v_ashrrev_i32_e32 v1, 31, v0
	v_lshlrev_b64 v[0:1], 5, v[0:1]
	v_lshl_add_u64 v[0:1], s[54:55], 0, v[0:1]
	global_load_dwordx4 v[28:31], v[0:1], off
	global_load_dwordx4 v[12:15], v[0:1], off offset:16
	v_add_u32_e32 v0, s7, v175
	v_ashrrev_i32_e32 v1, 31, v0
	v_lshlrev_b64 v[0:1], 5, v[0:1]
	v_lshl_add_u64 v[0:1], s[54:55], 0, v[0:1]
	global_load_dwordx4 v[24:27], v[0:1], off
	global_load_dwordx4 v[8:11], v[0:1], off offset:16
	v_add_u32_e32 v0, s7, v182
	v_ashrrev_i32_e32 v1, 31, v0
	v_lshlrev_b64 v[0:1], 5, v[0:1]
	v_lshl_add_u64 v[0:1], s[54:55], 0, v[0:1]
	global_load_dwordx4 v[20:23], v[0:1], off
	global_load_dwordx4 v[4:7], v[0:1], off offset:16
	v_add_u32_e32 v0, s7, v183
	v_ashrrev_i32_e32 v1, 31, v0
	v_lshlrev_b64 v[0:1], 5, v[0:1]
	v_lshl_add_u64 v[0:1], s[54:55], 0, v[0:1]
	global_load_dwordx4 v[16:19], v[0:1], off
	s_nop 0
	global_load_dwordx4 v[0:3], v[0:1], off offset:16
	s_and_saveexec_b64 s[0:1], s[36:37]
	ds_write_b32 v185, v65
	s_or_b64 exec, exec, s[0:1]
	s_waitcnt vmcnt(0) lgkmcnt(0)
	s_barrier
	s_and_saveexec_b64 s[0:1], s[38:39]
	v_mov_b32_e32 v32, s21
	v_mov_b32_e32 v33, -1
	ds_write_b32 v32, v33
	s_or_b64 exec, exec, s[0:1]
	v_add_u32_e32 v34, s6, v186
	v_mov_b64_e32 v[32:33], s[52:53]
	v_mad_i64_i32 v[32:33], s[0:1], v34, s4, v[32:33]
	v_lshl_add_u64 v[32:33], v[32:33], 0, v[64:65]
	s_mov_b64 s[0:1], 0x1000
	s_sub_i32 s9, s2, s59
	v_lshl_add_u64 v[138:139], v[32:33], 0, s[0:1]
	s_lshl_b32 s0, s9, 6
	v_mad_i64_i32 v[32:33], s[6:7], s0, v211, v[138:139]
	global_load_dwordx4 v[32:35], v[32:33], off
	s_sub_i32 s1, s62, s60
	s_sub_i32 s2, s5, s9
	s_min_i32 s35, s2, s1
	s_cmp_lt_i32 s35, 1
	s_waitcnt vmcnt(0) lgkmcnt(0)
	ds_write_b128 v187, v[32:35]
	s_waitcnt lgkmcnt(0)
	s_barrier
	s_cbranch_scc1 .LBB0_1067
	v_add_u32_e32 v223, s3, v174
	v_add_u32_e32 v224, s3, v175
	v_add_u32_e32 v225, s3, v182
	v_add_u32_e32 v226, s3, v183
	s_lshl_b32 s1, s59, 6
	s_lshl_b32 s2, s60, 6
	s_lshl_b32 s3, s18, 6
	s_add_i32 s63, s35, s9
	v_pk_mul_f32 v[140:141], v[30:31], 0.5 op_sel_hi:[1,0]
	v_pk_mul_f32 v[142:143], v[28:29], 0.5 op_sel_hi:[1,0]
	v_pk_mul_f32 v[144:145], v[14:15], 0.5 op_sel_hi:[1,0]
	v_pk_mul_f32 v[146:147], v[12:13], 0.5 op_sel_hi:[1,0]
	v_pk_mul_f32 v[148:149], v[26:27], 0.5 op_sel_hi:[1,0]
	v_pk_mul_f32 v[150:151], v[24:25], 0.5 op_sel_hi:[1,0]
	v_pk_mul_f32 v[152:153], v[10:11], 0.5 op_sel_hi:[1,0]
	v_pk_mul_f32 v[154:155], v[8:9], 0.5 op_sel_hi:[1,0]
	v_pk_mul_f32 v[156:157], v[22:23], 0.5 op_sel_hi:[1,0]
	v_pk_mul_f32 v[158:159], v[20:21], 0.5 op_sel_hi:[1,0]
	v_pk_mul_f32 v[160:161], v[6:7], 0.5 op_sel_hi:[1,0]
	v_pk_mul_f32 v[162:163], v[4:5], 0.5 op_sel_hi:[1,0]
	v_pk_mul_f32 v[164:165], v[18:19], 0.5 op_sel_hi:[1,0]
	v_pk_mul_f32 v[166:167], v[16:17], 0.5 op_sel_hi:[1,0]
	v_pk_mul_f32 v[168:169], v[2:3], 0.5 op_sel_hi:[1,0]
	v_pk_mul_f32 v[170:171], v[0:1], 0.5 op_sel_hi:[1,0]
	v_subrev_u32_e32 v227, s1, v172
	s_sub_i32 s66, s2, s3
	v_subrev_u32_e32 v228, s0, v216
	s_sub_i32 s67, 64, s1
	s_mov_b32 s70, 0
	s_mov_b32 s71, 0
	s_mov_b32 s72, 0
	s_mov_b32 s73, 0
	v_mov_b32_e32 v231, v184
	v_mov_b32_e32 v229, v184
	v_mov_b32_e32 v230, v184
	v_mov_b32_e32 v232, v184
	v_mov_b32_e32 v233, v184
	v_mov_b32_e32 v234, v184
	v_mov_b32_e32 v235, v184
	v_mov_b32_e32 v236, v184
	s_mov_b32 s74, 0
	s_mov_b32 s75, 0
	s_mov_b32 s76, 0
	s_mov_b32 s77, 0
	s_mov_b32 s78, 0
	s_mov_b32 s61, 0
	s_mov_b32 s16, 0
	s_mov_b32 s15, 0
	s_mov_b32 s8, 0
	s_mov_b32 s14, 0
	s_mov_b32 s13, 0
	s_mov_b32 s5, 0
	s_mov_b32 s68, 0
	v_lshrrev_b32_e32 v243, 5, v66
	v_lshlrev_b32_e32 v243, 12, v243
	s_add_i32 s0, s33, 0x0
	v_add_u32_e32 v248, s0, v243
	v_mov_b32_e32 v238, v248
	s_add_i32 s0, s33, 0x800
	v_add_u32_e32 v249, s0, v243
	v_mov_b32_e32 v239, v249
	s_add_i32 s0, s33, 0x2000
	v_add_u32_e32 v250, s0, v243
	v_mov_b32_e32 v240, v250
	s_add_i32 s0, s33, 0x2800
	v_add_u32_e32 v237, s0, v243
	v_mov_b32_e32 v241, v237
	v_cndmask_b32_e64 v242, 0, -1, s[40:41]
	v_cndmask_b32_e64 v188, v230, v231, s[40:41]
	v_cndmask_b32_e64 v189, v232, v229, s[40:41]
	v_cndmask_b32_e64 v190, v235, v233, s[40:41]
	v_cndmask_b32_e64 v191, v236, v234, s[40:41]

.LBB0_1960:
	s_add_u32 s51, s44, 0x2f000000
	s_addc_u32 s52, s45, 0
	s_and_b64 s[0:1], s[0:1], exec
	s_cselect_b32 s53, 0, 0x2000
	s_add_i32 s10, s18, s53
	s_cmpk_lt_i32 s18, 0x2000
	s_cselect_b64 s[0:1], -1, 0
	s_and_b64 s[2:3], s[0:1], exec
	s_cselect_b32 s2, s10, 0x4000
	v_mov_b32_e32 v0, -1
	s_cmpk_gt_i32 s2, 0x3fff
	v_mov_b32_e32 v1, -1
	v_mov_b32_e32 v2, -1
	s_movk_i32 s79, 0xff
	s_movk_i32 s80, 0xe000
	s_cbranch_scc1 .LBB0_1965
	s_bfe_u32 s23, s2, 0x70006
	s_add_i32 s3, s23, 1
	s_ashr_i32 s22, s2, 13
	s_sub_i32 s25, 0x7f, s23
	s_mul_i32 s25, s25, 0x82
	s_add_i32 s25, s25, 1
	s_mul_i32 s11, s23, 0x81
	s_cmpk_lt_u32 s23, 0x40
	s_cselect_b32 s11, s11, s25
	s_and_b32 s24, s2, 63
	s_mul_i32 s2, s22, 0x2040
	s_add_i32 s11, s11, s2
	s_add_i32 s2, s11, s3
	s_ashr_i32 s3, s2, 31
	s_mul_i32 s3, s3, s5
	s_mul_hi_u32 s25, s2, s5
	s_add_i32 s25, s25, s3
	s_mul_i32 s2, s2, s5
	s_add_u32 s2, s2, -1
	s_addc_u32 s3, s25, -1
	s_mul_hi_u32 s25, s2, 0xfe03f8
	s_mul_i32 s34, s2, 0xfe03f8
	s_mul_i32 s36, s3, 0xfe03f81
	s_mul_hi_u32 s2, s2, 0xfe03f81
	s_mul_hi_u32 s35, s3, 0xfe03f81
	s_add_u32 s2, s36, s2
	s_addc_u32 s35, s35, 0
	s_add_u32 s2, s34, s2
	s_addc_u32 s2, s25, 0
	s_add_u32 s2, s35, s2
	s_addc_u32 s25, 0, 0
	s_mul_i32 s35, s3, 0xfe03f8
	s_mul_hi_u32 s34, s3, 0xfe03f8
	s_add_u32 s2, s35, s2
	s_addc_u32 s25, s34, s25
	s_ashr_i32 s3, s3, 31
	s_mul_i32 s34, s3, 0xfe03f8
	s_mul_hi_u32 s35, s3, 0xfe03f81
	s_add_i32 s34, s35, s34
	s_mul_i32 s3, s3, 0xfe03f81
	s_add_i32 s34, s34, s3
	s_add_u32 s2, s2, s3
	s_addc_u32 s3, s25, s34
	s_lshr_b32 s25, s3, 31
	s_lshr_b64 s[2:3], s[2:3], 6
	s_add_i32 s25, s2, s25
	s_add_i32 s2, s11, 1
	s_ashr_i32 s3, s2, 31
	s_mul_i32 s3, s3, s5
	s_mul_hi_u32 s11, s2, s5
	s_add_i32 s11, s11, s3
	s_mul_i32 s2, s2, s5
	s_add_u32 s3, s2, -1
	s_addc_u32 s34, s11, -1
	s_mul_hi_u32 s35, s3, 0xff01fc07
	s_mul_i32 s36, s3, 0xff01fc07
	s_mul_i32 s38, s34, 0xf01fc07f
	s_mul_hi_u32 s3, s3, 0xf01fc07f
	s_mul_hi_u32 s37, s34, 0xf01fc07f
	s_add_u32 s3, s38, s3
	s_addc_u32 s37, s37, 0
	s_add_u32 s3, s36, s3
	s_addc_u32 s3, s35, 0
	s_add_u32 s3, s37, s3
	s_addc_u32 s35, 0, 0
	s_mul_i32 s37, s34, 0xff01fc07
	s_mul_hi_u32 s36, s34, 0xff01fc07
	s_add_u32 s3, s37, s3
	s_addc_u32 s35, s36, s35
	s_ashr_i32 s34, s34, 31
	s_mul_i32 s36, s34, 0xff01fc07
	s_mul_hi_u32 s37, s34, 0xf01fc07f
	s_add_i32 s36, s37, s36
	s_mul_i32 s34, s34, 0xf01fc07f
	s_add_i32 s36, s36, s34
	s_sub_u32 s2, s34, s2
	s_subb_u32 s11, s36, s11
	s_add_u32 s2, s2, s3
	s_addc_u32 s3, s11, s35
	s_add_u32 s2, s2, 1
	s_addc_u32 s3, s3, 0
	s_lshr_b32 s11, s3, 31
	s_lshr_b64 s[2:3], s[2:3], 6
	s_add_i32 s11, s2, s11
	s_lshl_b32 s2, s22, 7
	s_or_b32 s2, s2, s23
	s_mul_i32 s2, s2, 3
	s_ashr_i32 s3, s2, 31
	s_add_i32 s11, s11, s25
	s_lshl_b64 s[2:3], s[2:3], 8
	s_add_u32 s2, s51, s2
	s_addc_u32 s3, s52, s3
	s_lshl_b32 s22, s24, 2
	s_add_u32 s2, s2, s22
	s_addc_u32 s3, s3, 0
	v_mov_b64_e32 v[0:1], s[2:3]
	global_load_dword v2, v[0:1], off
	v_mov_b32_e32 v0, -1
	s_cmp_lt_i32 s11, 1
	v_mov_b32_e32 v1, -1
	s_cbranch_scc1 .LBB0_1963
	v_mov_b64_e32 v[4:5], s[2:3]
	global_load_dword v1, v[4:5], off offset:256

.LBB0_1977:
	s_cmpk_gt_i32 s59, 0x1fff
	s_cselect_b64 s[6:7], -1, 0
	s_add_i32 s0, s59, s53
	s_cmpk_lt_i32 s59, 0x2000
	s_cselect_b32 s10, s0, 0x4000
	v_mov_b32_e32 v239, -1
	s_cmpk_gt_i32 s10, 0x3fff
	v_mov_b32_e32 v240, -1
	v_mov_b32_e32 v238, -1
	s_cbranch_scc1 .LBB0_1982
	s_bfe_u32 s23, s10, 0x70006
	s_add_i32 s1, s23, 1
	s_ashr_i32 s22, s10, 13
	s_sub_i32 s25, 0x7f, s23
	s_mul_i32 s25, s25, 0x82
	s_add_i32 s25, s25, 1
	s_mul_i32 s11, s23, 0x81
	s_cmpk_lt_u32 s23, 0x40
	s_cselect_b32 s11, s11, s25
	s_mul_i32 s0, s22, 0x2040
	s_add_i32 s11, s11, s0
	s_add_i32 s0, s11, s1
	s_ashr_i32 s1, s0, 31
	s_mul_i32 s1, s1, s5
	s_mul_hi_u32 s25, s0, s5
	s_and_b32 s24, s10, 63
	s_add_i32 s25, s25, s1
	s_mul_i32 s0, s0, s5
	s_add_u32 s0, s0, -1
	s_addc_u32 s1, s25, -1
	s_mul_hi_u32 s25, s0, 0xfe03f8
	s_mul_i32 s34, s0, 0xfe03f8
	s_mul_i32 s60, s1, 0xfe03f81
	s_mul_hi_u32 s0, s0, 0xfe03f81
	s_mul_hi_u32 s35, s1, 0xfe03f81
	s_add_u32 s0, s60, s0
	s_addc_u32 s35, s35, 0
	s_add_u32 s0, s34, s0
	s_addc_u32 s0, s25, 0
	s_add_u32 s0, s35, s0
	s_addc_u32 s25, 0, 0
	s_mul_i32 s35, s1, 0xfe03f8
	s_mul_hi_u32 s34, s1, 0xfe03f8
	s_add_u32 s0, s35, s0
	s_addc_u32 s25, s34, s25
	s_ashr_i32 s1, s1, 31
	s_mul_i32 s34, s1, 0xfe03f8
	s_mul_hi_u32 s35, s1, 0xfe03f81
	s_add_i32 s34, s35, s34
	s_mul_i32 s1, s1, 0xfe03f81
	s_add_i32 s34, s34, s1
	s_add_u32 s0, s0, s1
	s_addc_u32 s1, s25, s34
	s_lshr_b32 s25, s1, 31
	s_lshr_b64 s[0:1], s[0:1], 6
	s_add_i32 s25, s0, s25
	s_add_i32 s0, s11, 1
	s_ashr_i32 s1, s0, 31
	s_mul_i32 s1, s1, s5
	s_mul_hi_u32 s11, s0, s5
	s_add_i32 s11, s11, s1
	s_mul_i32 s0, s0, s5
	s_add_u32 s1, s0, -1
	s_addc_u32 s34, s11, -1
	s_mul_hi_u32 s35, s1, 0xff01fc07
	s_mul_i32 s60, s1, 0xff01fc07
	s_mul_i32 s62, s34, 0xf01fc07f
	s_mul_hi_u32 s1, s1, 0xf01fc07f
	s_mul_hi_u32 s61, s34, 0xf01fc07f
	s_add_u32 s1, s62, s1
	s_addc_u32 s61, s61, 0
	s_add_u32 s1, s60, s1
	s_addc_u32 s1, s35, 0
	s_add_u32 s1, s61, s1
	s_addc_u32 s35, 0, 0
	s_mul_i32 s61, s34, 0xff01fc07
	s_mul_hi_u32 s60, s34, 0xff01fc07
	s_add_u32 s1, s61, s1
	s_addc_u32 s35, s60, s35
	s_ashr_i32 s34, s34, 31
	s_mul_i32 s60, s34, 0xff01fc07
	s_mul_hi_u32 s61, s34, 0xf01fc07f
	s_add_i32 s60, s61, s60
	s_mul_i32 s34, s34, 0xf01fc07f
	s_add_i32 s60, s60, s34
	s_sub_u32 s0, s34, s0
	s_subb_u32 s11, s60, s11
	s_add_u32 s0, s0, s1
	s_addc_u32 s1, s11, s35
	s_add_u32 s0, s0, 1
	s_addc_u32 s1, s1, 0
	s_lshr_b32 s11, s1, 31
	s_lshr_b64 s[0:1], s[0:1], 6
	s_add_i32 s11, s0, s11
	s_lshl_b32 s0, s22, 7
	s_or_b32 s0, s0, s23
	s_mul_i32 s0, s0, 3
	s_ashr_i32 s1, s0, 31
	s_add_i32 s11, s11, s25
	s_lshl_b64 s[0:1], s[0:1], 8
	s_add_u32 s0, s51, s0
	s_addc_u32 s1, s52, s1
	s_lshl_b32 s22, s24, 2
	s_add_u32 s0, s0, s22
	s_addc_u32 s1, s1, 0
	v_mov_b64_e32 v[18:19], s[0:1]
	global_load_dword v238, v[18:19], off
	v_mov_b32_e32 v239, -1
	s_cmp_lt_i32 s11, 1
	v_mov_b32_e32 v240, -1
	s_cbranch_scc1 .LBB0_1980
	v_mov_b64_e32 v[18:19], s[0:1]
	global_load_dword v240, v[18:19], off offset:256
